# FoX: QK half issues the whole S0 accumulator chain (4 QK + sigma MFMA) before S1, so the late C-operand reads of S1 land behind 5 MFMAs
# baseline (speedup 1.0000x reference)
.Lfx_body:
	s_add_i32 s37, s49, 0x18000
	s_and_b32 s37, s37, 0xc000
	v_add_u32_e32 v1, s37, v189
	ds_read_b128 v[126:129], v1 offset:32768
	ds_read_b128 v[106:109], v1 offset:40960
	ds_read_b128 v[98:101], v1 offset:33792
	ds_read_b128 v[102:105], v1 offset:41984
	ds_read_b128 v[86:89], v1 offset:34816
	ds_read_b128 v[94:97], v1 offset:43008
	ds_read_b128 v[82:85], v1 offset:35840
	ds_read_b128 v[90:93], v1 offset:44032
	s_add_i32 s37, s49, 0xc000
	s_and_b32 s37, s37, 0xc000
	v_add_u32_e32 v194, s37, v189
	v_add_u32_e32 v195, 0xffffff00, v175
	v_max_i32_e32 v195, v195, v0
	v_mfma_f32_32x32x16_bf16 v[18:33], v[158:161], v[122:125], v[18:33]
	v_exp_f32_e32 v208, v34
	v_exp_f32_e32 v209, v35
	v_exp_f32_e32 v210, v36
	v_exp_f32_e32 v211, v37
	ds_read_b128 v[158:161], v194 offset:36864
	v_mfma_f32_32x32x16_bf16 v[18:33], v[154:157], v[118:121], v[18:33]
	v_exp_f32_e32 v212, v38
	v_exp_f32_e32 v213, v39
	v_exp_f32_e32 v214, v40
	v_exp_f32_e32 v215, v41
	ds_read_b128 v[154:157], v194 offset:37888
	v_mfma_f32_32x32x16_bf16 v[2:17], v[142:145], v[122:125], v[2:17]
	v_exp_f32_e32 v216, v42
	v_exp_f32_e32 v217, v43
	v_exp_f32_e32 v218, v44
	v_exp_f32_e32 v219, v45
	ds_read_b128 v[142:145], v194 offset:38912
	v_mfma_f32_32x32x16_bf16 v[18:33], v[150:153], v[114:117], v[18:33]
	v_exp_f32_e32 v220, v46
	v_exp_f32_e32 v221, v47
	v_exp_f32_e32 v222, v48
	v_exp_f32_e32 v223, v49
	ds_read_b128 v[150:153], v194 offset:45056
	ds_read_b128 v[34:37], v195
	ds_read_b128 v[38:41], v195 offset:16
	ds_read_b128 v[42:45], v195 offset:64
	ds_read_b128 v[46:49], v195 offset:80
	v_mfma_f32_32x32x16_bf16 v[2:17], v[138:141], v[118:121], v[2:17]
	v_exp_f32_e32 v224, v50
	v_exp_f32_e32 v225, v51
	v_exp_f32_e32 v226, v52
	v_exp_f32_e32 v227, v53
	ds_read_b128 v[138:141], v194 offset:39936
	v_mfma_f32_32x32x16_bf16 v[18:33], v[146:149], v[110:113], v[18:33]
	v_exp_f32_e32 v228, v54
	v_exp_f32_e32 v229, v55
	v_exp_f32_e32 v230, v56
	v_exp_f32_e32 v231, v57
	ds_read_b128 v[146:149], v194 offset:46080
	v_mfma_f32_32x32x16_bf16 v[2:17], v[134:137], v[114:117], v[2:17]
	v_exp_f32_e32 v244, v58
	v_exp_f32_e32 v245, v59
	v_exp_f32_e32 v246, v60
	v_exp_f32_e32 v247, v61
	ds_read_b128 v[134:137], v194 offset:47104
	v_mfma_f32_32x32x16_bf16 v[2:17], v[130:133], v[110:113], v[2:17]
	v_exp_f32_e32 v248, v62
	v_exp_f32_e32 v249, v63
	v_exp_f32_e32 v250, v64
	v_exp_f32_e32 v251, v65
	ds_read_b128 v[130:133], v194 offset:48128
	ds_read_b128 v[50:53], v195 offset:128
	ds_read_b128 v[54:57], v195 offset:144
	ds_read_b128 v[58:61], v195 offset:192
	ds_read_b128 v[62:65], v195 offset:208
	v_add_f32_e32 v110, v208, v209
	v_add_f32_e32 v111, v210, v211
	v_add_f32_e32 v112, v212, v213
	v_add_f32_e32 v113, v214, v215
	s_waitcnt lgkmcnt(8)
	v_mfma_f32_32x32x16_bf16 v[34:49], v[126:129], v[66:69], v[34:49]
	v_add_f32_e32 v110, v216, v110
	v_add_f32_e32 v111, v217, v111
	v_add_f32_e32 v112, v218, v112
	v_mfma_f32_32x32x16_bf16 v[34:49], v[98:101], v[70:73], v[34:49]
	v_add_f32_e32 v113, v219, v113
	v_add_f32_e32 v110, v220, v110
	v_add_f32_e32 v111, v221, v111
	v_mfma_f32_32x32x16_bf16 v[34:49], v[86:89], v[74:77], v[34:49]
	v_add_f32_e32 v112, v222, v112
	v_add_f32_e32 v113, v223, v113
	v_add_f32_e32 v110, v224, v110
	v_mfma_f32_32x32x16_bf16 v[34:49], v[82:85], v[78:81], v[34:49]
	v_add_f32_e32 v111, v225, v111
	v_add_f32_e32 v112, v226, v112
	v_add_f32_e32 v113, v227, v113
	v_mfma_f32_32x32x16_bf16 v[34:49], v[196:199], v[162:165], v[34:49]
	v_add_f32_e32 v110, v228, v110
	v_add_f32_e32 v111, v229, v111
	v_add_f32_e32 v112, v230, v112
	s_waitcnt lgkmcnt(0)
	v_mfma_f32_32x32x16_bf16 v[50:65], v[106:109], v[66:69], v[50:65]
	v_add_f32_e32 v113, v231, v113
	v_add_f32_e32 v110, v244, v110
	v_add_f32_e32 v111, v245, v111
	v_mfma_f32_32x32x16_bf16 v[50:65], v[102:105], v[70:73], v[50:65]
	v_add_f32_e32 v112, v246, v112
	v_add_f32_e32 v113, v247, v113
	v_add_f32_e32 v110, v248, v110
	v_mfma_f32_32x32x16_bf16 v[50:65], v[94:97], v[74:77], v[50:65]
	v_add_f32_e32 v111, v249, v111
	v_add_f32_e32 v112, v250, v112
	v_add_f32_e32 v113, v251, v113
	v_mfma_f32_32x32x16_bf16 v[50:65], v[90:93], v[78:81], v[50:65]
	v_mfma_f32_32x32x16_bf16 v[50:65], v[196:199], v[162:165], v[50:65]
	v_add_f32_e32 v110, v110, v111
	v_add_f32_e32 v112, v112, v113
	v_add_f32_e32 v114, v110, v112
	v_cmp_lt_f32_e32 vcc, 0x49800000, v114
	s_cbranch_vccnz .Lfx_rare
